# rwkv_post: y/gate/bonus loads issued at the top of the iteration together with the token-shift loads (one memory round trip per iteration instead of two)
# speedup vs baseline: 1.0256x; 1.0030x over previous
.LBB0_638:
	s_or_b64 exec, exec, s[10:11]
	s_waitcnt vmcnt(0)
	v_lshlrev_b64 v[10:11], 12, v[16:17]
	v_lshl_add_u64 v[10:11], v[24:25], 0, v[10:11]
	v_mov_b32_e32 v38, v240
	v_mov_b32_e32 v39, v241
	v_mov_b32_e32 v40, v242
	v_mov_b32_e32 v41, v243
	v_lshlrev_b64 v[10:11], 10, v[16:17]
	v_lshlrev_b64 v[42:43], 5, v[16:17]
	v_lshl_add_u64 v[10:11], v[20:21], 0, v[10:11]
	v_lshl_add_u64 v[42:43], v[18:19], 0, v[42:43]
	v_mov_b32_e32 v10, v244
	v_mov_b32_e32 v11, v245
	v_lshlrev_b64 v[46:47], 11, v[16:17]
	v_mov_b32_e32 v42, v246
	s_waitcnt vmcnt(3)
	v_lshlrev_b32_e32 v45, 16, v33
	v_lshlrev_b32_e32 v44, 16, v32
	v_and_b32_e32 v33, 0xffff0000, v33
	v_and_b32_e32 v32, 0xffff0000, v32
	v_pk_add_f32 v[12:13], v[12:13], v[32:33] neg_lo:[0,1] neg_hi:[0,1]
	v_pk_add_f32 v[6:7], v[6:7], v[44:45] neg_lo:[0,1] neg_hi:[0,1]
	v_pk_fma_f32 v[12:13], v[2:3], v[12:13], v[32:33]
	v_pk_fma_f32 v[6:7], v[8:9], v[6:7], v[44:45]
	s_add_i32 s16, s16, s33
	v_lshl_add_u64 v[46:47], v[26:27], 0, v[46:47]
	s_cmpk_lt_i32 s16, 0x2200
	v_add_u32_e32 v16, s0, v16
	s_waitcnt vmcnt(2)
	v_add_f32_e32 v17, v38, v39
	v_add_f32_e32 v17, v17, v40
	v_add_f32_e32 v17, v17, v41
	v_mov_b32_e32 v32, v38
	v_mov_b32_e32 v33, v40
	v_add_f32_dpp v17, v17, v17 quad_perm:[1,0,3,2] row_mask:0xf bank_mask:0xf bound_ctrl:1
	v_mov_b32_e32 v40, v39
	s_waitcnt vmcnt(1)
	v_lshlrev_b32_e32 v45, 16, v11
	v_add_f32_dpp v17, v17, v17 quad_perm:[2,3,0,1] row_mask:0xf bank_mask:0xf bound_ctrl:1
	v_lshlrev_b32_e32 v44, 16, v10
	v_and_b32_e32 v11, 0xffff0000, v11
	v_add_f32_dpp v17, v17, v17 row_half_mirror row_mask:0xf bank_mask:0xf bound_ctrl:1
	v_and_b32_e32 v10, 0xffff0000, v10
	s_nop 0
	v_add_f32_dpp v17, v17, v17 row_mirror row_mask:0xf bank_mask:0xf bound_ctrl:1
	v_mul_f32_e32 v38, 0x3c800000, v17
	v_pk_add_f32 v[32:33], v[32:33], v[38:39] op_sel_hi:[1,0] neg_lo:[0,1] neg_hi:[0,1]
	v_pk_add_f32 v[38:39], v[40:41], v[38:39] op_sel_hi:[1,0] neg_lo:[0,1] neg_hi:[0,1]
	v_mov_b32_e32 v40, v32
	v_mov_b32_e32 v41, v38
	v_mov_b32_e32 v48, v39
	v_mov_b32_e32 v49, v33
	v_pk_mul_f32 v[40:41], v[40:41], v[40:41]
	v_pk_mul_f32 v[48:49], v[48:49], v[48:49]
	v_add_f32_e32 v17, v40, v41
	v_add_f32_e32 v17, v49, v17
	v_add_f32_e32 v17, v48, v17
	s_nop 1
	v_add_f32_dpp v17, v17, v17 quad_perm:[1,0,3,2] row_mask:0xf bank_mask:0xf bound_ctrl:1
	s_nop 1
	v_add_f32_dpp v17, v17, v17 quad_perm:[2,3,0,1] row_mask:0xf bank_mask:0xf bound_ctrl:1
	s_nop 1
	v_add_f32_dpp v17, v17, v17 row_half_mirror row_mask:0xf bank_mask:0xf bound_ctrl:1
	s_nop 1
	v_add_f32_dpp v17, v17, v17 row_mirror row_mask:0xf bank_mask:0xf bound_ctrl:1
	v_fmamk_f32 v17, v17, 0x3c800000, v35
	v_mul_f32_e32 v37, 0x4b800000, v17
	v_cmp_gt_f32_e32 vcc, s20, v17
	s_nop 1
	v_cndmask_b32_e32 v17, v17, v37, vcc
	v_rsq_f32_e32 v17, v17
	s_nop 0
	v_mul_f32_e32 v37, 0x45800000, v17
	v_cndmask_b32_e32 v40, v17, v37, vcc
	v_pk_mul_f32 v[38:39], v[38:39], v[40:41] op_sel_hi:[1,0]
	v_pk_mul_f32 v[32:33], v[32:33], v[40:41] op_sel_hi:[1,0]
	v_pk_fma_f32 v[38:39], v[30:31], v[38:39], v[28:29]
	v_pk_fma_f32 v[32:33], v[4:5], v[32:33], v[0:1]
	s_waitcnt vmcnt(0)
	v_pk_fma_f32 v[12:13], v[12:13], v[42:43], v[38:39] op_sel_hi:[1,0,1]
	v_pk_fma_f32 v[6:7], v[6:7], v[42:43], v[32:33] op_sel_hi:[1,0,1]
	v_pk_mul_f32 v[10:11], v[12:13], v[10:11]
	v_pk_mul_f32 v[6:7], v[6:7], v[44:45]
	v_and_b32_sdwa v17, v11, v36 dst_sel:DWORD dst_unused:UNUSED_PAD src0_sel:WORD_1 src1_sel:DWORD
	v_and_b32_sdwa v32, v10, v36 dst_sel:DWORD dst_unused:UNUSED_PAD src0_sel:WORD_1 src1_sel:DWORD
	v_and_b32_sdwa v12, v7, v36 dst_sel:DWORD dst_unused:UNUSED_PAD src0_sel:WORD_1 src1_sel:DWORD
	v_and_b32_sdwa v13, v6, v36 dst_sel:DWORD dst_unused:UNUSED_PAD src0_sel:WORD_1 src1_sel:DWORD
	v_add3_u32 v11, v11, v17, s21
	v_add3_u32 v10, v10, v32, s21
	v_add3_u32 v6, v6, v13, s21
	v_add3_u32 v7, v7, v12, s21
	v_and_b32_e32 v11, 0xffff0000, v11
	v_and_b32_e32 v10, 0xffff0000, v10
	v_or_b32_sdwa v7, v11, v7 dst_sel:DWORD dst_unused:UNUSED_PAD src0_sel:DWORD src1_sel:WORD_1
	v_or_b32_sdwa v6, v10, v6 dst_sel:DWORD dst_unused:UNUSED_PAD src0_sel:DWORD src1_sel:WORD_1
	global_store_dwordx2 v[46:47], v[6:7], off offset:1024
	s_cbranch_scc0 .LBB0_644
.LBB0_639:
	v_ashrrev_i32_e32 v17, 31, v16
	v_lshlrev_b64 v[248:249], 12, v[16:17]
	v_lshl_add_u64 v[248:249], v[24:25], 0, v[248:249]
	global_load_dwordx4 v[240:243], v[248:249], off offset:2048
	v_lshlrev_b64 v[250:251], 10, v[16:17]
	v_lshl_add_u64 v[250:251], v[20:21], 0, v[250:251]
	global_load_dwordx2 v[244:245], v[250:251], off
	v_lshlrev_b64 v[252:253], 5, v[16:17]
	v_lshl_add_u64 v[252:253], v[18:19], 0, v[252:253]
	global_load_dword v246, v[252:253], off
	v_mad_i64_i32 v[10:11], s[10:11], v16, s14, v[22:23]
	global_load_dwordx2 v[32:33], v[10:11], off offset:3072
	v_cmp_gt_i32_e64 s[10:11], s3, v16
	v_cmp_lt_i32_e32 vcc, s1, v16
	s_nop 0
	v_cndmask_b32_e64 v6, 7, v34, s[10:11]
	v_and_b32_e32 v6, v6, v16
	v_cmp_ne_u32_e64 s[10:11], 0, v6
	s_and_saveexec_b64 s[12:13], s[10:11]
	s_xor_b64 s[10:11], exec, s[12:13]
	s_cbranch_execz .LBB0_641
	global_load_dwordx2 v[10:11], v[10:11], off offset:-1536
	s_waitcnt vmcnt(0)
	v_lshlrev_b32_e32 v6, 16, v10
	v_and_b32_e32 v12, 0xffff0000, v10
	v_lshlrev_b32_e32 v7, 16, v11
	v_and_b32_e32 v13, 0xffff0000, v11
